# XCD leaders no longer bump the per-XCD generation word nor wait for the generation-add acks before releasing their own workgroup
# baseline (speedup 1.0000x reference)
; __device__ __forceinline__ unsigned xb_ld(unsigned* p)              { return __hip_atomic_load(p, __ATOMIC_RELAXED, __HIP_MEMORY_SCOPE_AGENT); }
; __device__ __forceinline__ unsigned xb_add(unsigned* p, unsigned v) { return __hip_atomic_fetch_add(p, v, __ATOMIC_RELAXED, __HIP_MEMORY_SCOPE_AGENT); }
; #define XB_SPIN(cond, bar) do { unsigned _sp = 0; while (cond) { __builtin_amdgcn_s_sleep(1); \
;     if ((++_sp & 255u) == 0u) { if (xb_ld(&(bar)[XB_TMO])) break; if (_sp > XB_SPIN_CAP) { atomicAdd(&(bar)[XB_TMO], 1u); break; } } } } while (0)
; __device__ __forceinline__ void xcd_barrier(const XcdBarrier& b) {
;     ...
;             if (og + 1u == (tg + 1u) * nx) xb_add(&bar[XB_TOPGEN], 1u);
;             else XB_SPIN(xb_ld(&bar[XB_TOPGEN]) == tg, bar);
;             __builtin_amdgcn_fence(__ATOMIC_ACQUIRE, "agent");
;             xb_add(&bar[XB_XGEN(b.x)], 1u);
;             asm volatile("s_waitcnt vmcnt(0)" ::: "memory");
;         } else {
;             XB_SPIN(xb_ld(&bar[XB_XGEN(b.x)]) == gen, bar);
;             __builtin_amdgcn_fence(__ATOMIC_ACQUIRE, "agent");
;             asm volatile("s_waitcnt vmcnt(0)" ::: "memory");
;         }
;     }
;     __syncthreads();
.LBB0_146:
.LBB0_147:
	s_or_b64 exec, exec, s[2:3]
	s_waitcnt lgkmcnt(0)
	s_barrier

; __device__ __forceinline__ unsigned xb_ld(unsigned* p)              { return __hip_atomic_load(p, __ATOMIC_RELAXED, __HIP_MEMORY_SCOPE_AGENT); }
; __device__ __forceinline__ unsigned xb_add(unsigned* p, unsigned v) { return __hip_atomic_fetch_add(p, v, __ATOMIC_RELAXED, __HIP_MEMORY_SCOPE_AGENT); }
; #define XB_SPIN(cond, bar) do { unsigned _sp = 0; while (cond) { __builtin_amdgcn_s_sleep(1); \
;     if ((++_sp & 255u) == 0u) { if (xb_ld(&(bar)[XB_TMO])) break; if (_sp > XB_SPIN_CAP) { atomicAdd(&(bar)[XB_TMO], 1u); break; } } } } while (0)
; __device__ __forceinline__ void xcd_barrier(const XcdBarrier& b) {
;     ...
;             if (og + 1u == (tg + 1u) * nx) xb_add(&bar[XB_TOPGEN], 1u);
;             else XB_SPIN(xb_ld(&bar[XB_TOPGEN]) == tg, bar);
;             __builtin_amdgcn_fence(__ATOMIC_ACQUIRE, "agent");
;             xb_add(&bar[XB_XGEN(b.x)], 1u);
;             asm volatile("s_waitcnt vmcnt(0)" ::: "memory");
;         } else {
;             XB_SPIN(xb_ld(&bar[XB_XGEN(b.x)]) == gen, bar);
;             __builtin_amdgcn_fence(__ATOMIC_ACQUIRE, "agent");
;             asm volatile("s_waitcnt vmcnt(0)" ::: "memory");
;         }
;     }
;     __syncthreads();
.LBB0_1848:
.LBB0_1849:
	s_or_b64 exec, exec, s[0:1]
	s_waitcnt lgkmcnt(0)
	s_barrier

; __device__ __forceinline__ unsigned xb_ld(unsigned* p)              { return __hip_atomic_load(p, __ATOMIC_RELAXED, __HIP_MEMORY_SCOPE_AGENT); }
; __device__ __forceinline__ unsigned xb_add(unsigned* p, unsigned v) { return __hip_atomic_fetch_add(p, v, __ATOMIC_RELAXED, __HIP_MEMORY_SCOPE_AGENT); }
; #define XB_SPIN(cond, bar) do { unsigned _sp = 0; while (cond) { __builtin_amdgcn_s_sleep(1); \
;     if ((++_sp & 255u) == 0u) { if (xb_ld(&(bar)[XB_TMO])) break; if (_sp > XB_SPIN_CAP) { atomicAdd(&(bar)[XB_TMO], 1u); break; } } } } while (0)
;     constexpr int RL = 2048 * NC;
;     for (int r = gw; r < R; r += NGW) { const bf16_t* sr = src + (size_t)r * RL; u32x4 pk[NC][4]; float mx = 0.f;
;         float sq = 0.f; if constexpr (RGN) sq = ssq[(size_t)r * 64 + lane];
; __device__ __forceinline__ void xcd_barrier(const XcdBarrier& b) {
;     ...
;             if (og + 1u == (tg + 1u) * nx) xb_add(&bar[XB_TOPGEN], 1u);
;             else XB_SPIN(xb_ld(&bar[XB_TOPGEN]) == tg, bar);
;             __builtin_amdgcn_fence(__ATOMIC_ACQUIRE, "agent");
;             xb_add(&bar[XB_XGEN(b.x)], 1u);
;             asm volatile("s_waitcnt vmcnt(0)" ::: "memory");
;         } else {
;             XB_SPIN(xb_ld(&bar[XB_XGEN(b.x)]) == gen, bar);
;             __builtin_amdgcn_fence(__ATOMIC_ACQUIRE, "agent");
;             asm volatile("s_waitcnt vmcnt(0)" ::: "memory");
;         }
;     }
;     __syncthreads();
.LBB0_2161:
.LBB0_2162:
	s_or_b64 exec, exec, s[2:3]
	s_cmpk_gt_i32 s6, 0x21ff
	s_waitcnt lgkmcnt(0)
	s_barrier
	s_cbranch_scc1 .LBB0_2167
	v_mbcnt_lo_u32_b32 v1, -1, 0
	s_waitcnt vmcnt(0)
	v_mbcnt_hi_u32_b32 v2, -1, v1
	v_and_b32_e32 v1, 64, v2
	v_add_u32_e32 v3, 64, v1
	v_xor_b32_e32 v1, 1, v2
	v_cmp_lt_i32_e32 vcc, v1, v3
	v_xor_b32_e32 v4, 2, v2
	s_ashr_i32 s7, s6, 31
	v_cndmask_b32_e32 v1, v2, v1, vcc
	v_cmp_lt_i32_e32 vcc, v4, v3
	s_lshl_b64 s[2:3], s[6:7], 2
	s_add_u32 s17, s2, 0x5af0f000
	v_cndmask_b32_e32 v4, v2, v4, vcc
	v_lshlrev_b32_e32 v16, 2, v4
	v_xor_b32_e32 v4, 4, v2
	v_cmp_lt_i32_e32 vcc, v4, v3
	s_addc_u32 s20, s3, 0
	s_lshl_b64 s[10:11], s[6:7], 8
	v_cndmask_b32_e32 v4, v2, v4, vcc
	v_lshlrev_b32_e32 v17, 2, v4
	v_xor_b32_e32 v4, 8, v2
	v_cmp_lt_i32_e32 vcc, v4, v3
	s_ashr_i32 s9, s8, 31
	s_lshl_b64 s[12:13], s[6:7], 13
	v_cndmask_b32_e32 v4, v2, v4, vcc
	v_lshlrev_b32_e32 v18, 2, v4
	v_xor_b32_e32 v4, 16, v2
	v_cmp_lt_i32_e32 vcc, v4, v3
	s_lshl_b64 s[14:15], s[6:7], 12
	v_cmp_eq_u32_e64 s[4:5], 0, v238
	v_cndmask_b32_e32 v4, v2, v4, vcc
	v_lshlrev_b32_e32 v19, 2, v4
	v_xor_b32_e32 v4, 32, v2
	v_cmp_lt_i32_e32 vcc, v4, v3
	v_mov_b32_e32 v3, s11
	v_lshlrev_b32_e32 v1, 2, v1
	v_cndmask_b32_e32 v2, v2, v4, vcc
	v_lshlrev_b32_e32 v20, 2, v2
	v_lshl_or_b32 v2, v238, 2, s10
	s_mov_b64 s[10:11], 0x52db9000
	s_lshl_b64 s[2:3], s[8:9], 2
	v_lshl_add_u64 v[10:11], v[2:3], 0, s[10:11]
	s_lshl_b64 s[10:11], s[8:9], 8
	v_lshl_or_b32 v12, v238, 4, s12
	v_mov_b32_e32 v13, s13
	s_lshl_b64 s[12:13], s[8:9], 13
	v_lshl_or_b32 v14, v238, 3, s14
	v_mov_b32_e32 v15, s15
	s_lshl_b64 s[14:15], s[8:9], 12
	s_mov_b32 s7, 0x1950f000
	v_mov_b32_e32 v21, 0x358637bd
	s_mov_b32 s9, 0x800000
	v_mov_b32_e32 v22, 0
	s_mov_b32 s21, 0x42fe0000
	s_mov_b32 s16, 0x4b400000
	s_mov_b32 s22, 0x2830f000
	s_branch .LBB0_2165
